# attention: softmax VALU spread over QK MFMA gaps, max/vote/scale hoisted into PV gaps, SGPR-base K/V loads in odd-tile body (no per-load 64-bit VALU address chain), 16-row K LDS swizzle
# baseline (speedup 1.0000x reference)
; __global__ void __launch_bounds__(mk::NTHR, 2) fwd_kernel(Args args) {
;     ...
;     if (IN(13)) {
;         for (int u = vcu; u < 1024; u += G) { const int qb = u & 31, gq = (u >> 5) & 3, kvh = (u >> 7) & 1, b = u >> 8, h = kvh * 4 + gq;
.LBB0_1582:
	s_cmp_lt_i32 s84, 14
	s_cselect_b64 s[4:5], -1, 0
	s_and_b64 s[28:29], s[4:5], s[2:3]
	s_xor_b64 s[2:3], s[28:29], -1
	s_cmpk_gt_i32 s33, 0x3ff
	s_cselect_b64 s[4:5], -1, 0
	s_or_b64 s[2:3], s[2:3], s[4:5]
	s_and_b64 vcc, exec, s[2:3]
	s_cbranch_vccnz .LBB0_1602
	v_readfirstlane_b32 s98, v0
	s_bitcmp1_b32 s98, 8
	s_cbranch_scc0 .Lattn_noprio
	s_nop 0
